# S34: S33 + attention epilogue: the four subln_w global loads issued together with one vmcnt wait instead of four serial round trips
# speedup vs baseline: 1.0092x; 1.0025x over previous
; __device__ __forceinline__ unsigned f2bf(float f) { unsigned u = __builtin_bit_cast(unsigned, f); return (u + 0x7fffu + ((u >> 16) & 1u)) >> 16; }
; __device__ __forceinline__ int crow(int r, int hi) { return (r & 3) + 8 * (r >> 2) + 4 * hi; }
; __device__ __forceinline__ void attn_unit(const bf16* __restrict__ Qb, const bf16* __restrict__ Kh, const bf16* __restrict__ Vh, int klat0, int nlt, int kctx0, int NT,
;                                           float lam, float post, const float* __restrict__ subw, bf16* __restrict__ Ob, char* lds) {
;     ...
;     float sw[4];
; #pragma unroll
;     for (int d0 = 0; d0 < 4; ++d0) sw[d0] = subw[d0 * 32 + r32_e] * post;
;     bf16* Ow = Ob + (long)(wq_e * 32) * DM;
; #pragma unroll
;     for (int r = 0; r < 16; ++r) { const int orow = crow(r, hi_e); float v[4]; float ss = 0.f;
; #pragma unroll
;       for (int d0 = 0; d0 < 4; ++d0) { v[d0] = o[d0][r] - lam * X[(wq_e * 32 + orow) * 128 + d0 * 32 + r32_e]; ss += v[d0] * v[d0]; }
;       ss += __shfl_xor(ss, 1); ss += __shfl_xor(ss, 2); ss += __shfl_xor(ss, 4); ss += __shfl_xor(ss, 8); ss += __shfl_xor(ss, 16);
;       const float rs = 1.0f / sqrtf(ss * (1.0f / 128.0f) + LN_EPS);
; #pragma unroll
;       for (int d0 = 0; d0 < 4; ++d0) Ow[(long)orow * DM + d0 * 32 + r32_e] = (bf16)f2bf(v[d0] * rs * sw[d0]); }
.LBB0_795:
	s_andn2_b64 vcc, exec, s[6:7]
	s_waitcnt lgkmcnt(0)
	s_barrier
	s_cbranch_vccnz .LBB0_714
	v_lshlrev_b32_e32 v30, 2, v139
	v_ashrrev_i32_e32 v139, 31, v138
	v_lshl_add_u64 v[4:5], v[138:139], 2, s[2:3]
	global_load_dword v8, v[4:5], off
	global_load_dword v244, v[4:5], off offset:128
	global_load_dword v245, v[4:5], off offset:256
	global_load_dword v246, v[4:5], off offset:384
	s_lshl_b64 s[0:1], s[4:5], 12
	v_readlane_b32 s4, v251, 21
	s_add_u32 s0, s4, s0
	v_readlane_b32 s4, v251, 22
	s_addc_u32 s1, s4, s1
	s_mov_b32 s4, 0xf800000
	s_add_u32 s0, s0, s16
	s_addc_u32 s1, s1, 0
	v_ashrrev_i32_e32 v31, 31, v30
	v_add_u32_e32 v28, 8, v30
	v_add_u32_e32 v26, 9, v30
	v_add_u32_e32 v24, 10, v30
	v_add_u32_e32 v22, 11, v30
	v_add_u32_e32 v20, 16, v30
	v_add_u32_e32 v18, 17, v30
	v_add_u32_e32 v16, 18, v30
	v_add_u32_e32 v14, 19, v30
	v_add_u32_e32 v12, 24, v30
	v_add_u32_e32 v10, 25, v30
	v_add_u32_e32 v6, 26, v30
	v_add_u32_e32 v2, 27, v30
	v_ashrrev_i32_e32 v29, 31, v28
	v_ashrrev_i32_e32 v27, 31, v26
	v_ashrrev_i32_e32 v25, 31, v24
	v_ashrrev_i32_e32 v23, 31, v22
	v_ashrrev_i32_e32 v21, 31, v20
	v_ashrrev_i32_e32 v19, 31, v18
	v_ashrrev_i32_e32 v17, 31, v16
	v_ashrrev_i32_e32 v15, 31, v14
	v_ashrrev_i32_e32 v13, 31, v12
	v_ashrrev_i32_e32 v11, 31, v10
	v_ashrrev_i32_e32 v7, 31, v6
	v_ashrrev_i32_e32 v3, 31, v2
	s_waitcnt vmcnt(0)
	v_mul_f32_e32 v34, v161, v8
	v_mul_f32_e32 v35, v161, v244
	v_mul_f32_e32 v36, v161, v245
	v_lshlrev_b32_e32 v8, 5, v88
	v_ashrrev_i32_e32 v9, 31, v8
	v_mul_f32_e32 v37, v161, v246
	v_lshlrev_b64 v[4:5], 12, v[8:9]
	v_add_u32_e32 v9, v30, v8
	v_lshl_add_u32 v9, v9, 7, v138
	v_lshl_add_u32 v9, v9, 2, 0
	ds_read2_b32 v[98:99], v9 offset1:32
	v_lshl_add_u64 v[4:5], s[0:1], 0, v[4:5]
	v_lshl_add_u64 v[4:5], v[138:139], 1, v[4:5]
	s_waitcnt lgkmcnt(0)
	v_fma_f32 v88, -v160, v98, v108
	v_fma_f32 v97, -v160, v99, v109
	ds_read2_b32 v[98:99], v9 offset0:64 offset1:96
	v_mul_f32_e32 v100, v97, v97
	v_fmac_f32_e32 v100, v88, v88
	s_waitcnt lgkmcnt(0)
	v_or_b32_e32 v245, 1, v30
	v_add_u32_e32 v244, v245, v8
	v_lshl_add_u32 v244, v244, 7, v138
	v_lshl_add_u32 v244, v244, 2, 0
	ds_read2_b32 v[240:241], v244 offset1:32
	ds_read2_b32 v[242:243], v244 offset0:64 offset1:96
	v_fma_f32 v9, -v160, v98, v106
	v_fmac_f32_e32 v100, v9, v9
	v_fma_f32 v101, -v160, v99, v107
	v_fmac_f32_e32 v100, v101, v101
	s_nop 1
	v_mov_b32_dpp v98, v100 quad_perm:[1,0,3,2] row_mask:0xf bank_mask:0xf
	v_add_f32_e32 v98, v100, v98
	s_nop 1
	v_mov_b32_dpp v99, v98 quad_perm:[2,3,0,1] row_mask:0xf bank_mask:0xf
	v_add_f32_e32 v98, v98, v99
	s_nop 1
	v_mov_b32_dpp v99, v98 row_half_mirror row_mask:0xf bank_mask:0xf
	v_add_f32_e32 v98, v98, v99
	s_nop 1
	v_mov_b32_dpp v99, v98 row_mirror row_mask:0xf bank_mask:0xf
	v_add_f32_e32 v98, v98, v99
	v_mov_b32_e32 v99, v98
	s_nop 1
	v_permlane16_swap_b32_e32 v98, v99
	v_add_f32_e32 v98, v98, v99
	v_fmamk_f32 v98, v98, 0x3c000000, v179
	v_cmp_gt_f32_e32 vcc, s4, v98
	v_mul_f32_e32 v99, 0x4f800000, v98
	s_nop 0
	v_cndmask_b32_e32 v98, v98, v99, vcc
	v_sqrt_f32_e32 v99, v98
	s_nop 0
	v_add_u32_e32 v100, -1, v99
	v_fma_f32 v102, -v100, v99, v98
	v_cmp_ge_f32_e64 s[0:1], 0, v102
	v_add_u32_e32 v102, 1, v99
	s_nop 0
	v_cndmask_b32_e64 v100, v99, v100, s[0:1]
	v_fma_f32 v99, -v102, v99, v98
	v_cmp_lt_f32_e64 s[0:1], 0, v99
	s_nop 1
	v_cndmask_b32_e64 v99, v100, v102, s[0:1]
	v_mul_f32_e32 v100, 0x37800000, v99
	v_cndmask_b32_e32 v99, v99, v100, vcc
	v_cmp_class_f32_e32 vcc, v98, v180
	s_nop 1
	v_cndmask_b32_e32 v98, v99, v98, vcc
	v_div_scale_f32 v99, s[0:1], v98, v98, 1.0
	v_rcp_f32_e32 v100, v99
	s_nop 0
	v_fma_f32 v102, -v99, v100, 1.0
	v_fmac_f32_e32 v100, v102, v100
	v_div_scale_f32 v102, vcc, 1.0, v98, 1.0
	v_mul_f32_e32 v103, v102, v100
	v_fma_f32 v104, -v99, v103, v102
	v_fmac_f32_e32 v103, v104, v100
	v_fma_f32 v99, -v99, v103, v102
	v_div_fmas_f32 v99, v99, v100, v103
	v_div_fixup_f32 v100, v99, v98, 1.0
	v_lshlrev_b64 v[98:99], 12, v[30:31]
	v_mul_f32_e32 v31, v88, v100
	v_mul_f32_e32 v31, v34, v31
	v_bfe_u32 v88, v31, 16, 1
	v_lshl_add_u64 v[98:99], v[4:5], 0, v[98:99]
	v_add3_u32 v31, v31, v88, s70
	global_store_short_d16_hi v[98:99], v31, off
	v_mul_f32_e32 v31, v97, v100
	v_mul_f32_e32 v31, v35, v31
	v_bfe_u32 v88, v31, 16, 1
	v_mul_f32_e32 v9, v9, v100
	v_add3_u32 v31, v31, v88, s70
	v_mul_f32_e32 v9, v36, v9
	global_store_short_d16_hi v[98:99], v31, off offset:64
	v_bfe_u32 v31, v9, 16, 1
	v_add3_u32 v9, v9, v31, s70
	global_store_short_d16_hi v[98:99], v9, off offset:128
	v_mul_f32_e32 v9, v101, v100
	v_mul_f32_e32 v9, v37, v9
	v_bfe_u32 v31, v9, 16, 1
	v_add3_u32 v9, v9, v31, s70
	global_store_short_d16_hi v[98:99], v9, off offset:192
	v_or_b32_e32 v98, 1, v30
	v_add_u32_e32 v9, v98, v8
	v_lshl_add_u32 v9, v9, 7, v138
	v_lshl_add_u32 v9, v9, 2, 0
	s_waitcnt lgkmcnt(1)
	v_fma_f32 v88, -v160, v241, v96
	v_fma_f32 v31, -v160, v240, v95
	v_mul_f32_e32 v95, v88, v88
	v_fmac_f32_e32 v95, v31, v31
	s_waitcnt lgkmcnt(0)
; __device__ __forceinline__ unsigned f2bf(float f) { unsigned u = __builtin_bit_cast(unsigned, f); return (u + 0x7fffu + ((u >> 16) & 1u)) >> 16; }
; __device__ __forceinline__ int crow(int r, int hi) { return (r & 3) + 8 * (r >> 2) + 4 * hi; }
; __device__ __forceinline__ void attn_unit(const bf16* __restrict__ Qb, const bf16* __restrict__ Kh, const bf16* __restrict__ Vh, int klat0, int nlt, int kctx0, int NT,
;                                           float lam, float post, const float* __restrict__ subw, bf16* __restrict__ Ob, char* lds) {
;     ...
;     for (int r = 0; r < 16; ++r) { const int orow = crow(r, hi_e); float v[4]; float ss = 0.f;
; #pragma unroll
;       for (int d0 = 0; d0 < 4; ++d0) { v[d0] = o[d0][r] - lam * X[(wq_e * 32 + orow) * 128 + d0 * 32 + r32_e]; ss += v[d0] * v[d0]; }
;       ss += __shfl_xor(ss, 1); ss += __shfl_xor(ss, 2); ss += __shfl_xor(ss, 4); ss += __shfl_xor(ss, 8); ss += __shfl_xor(ss, 16);
;       const float rs = 1.0f / sqrtf(ss * (1.0f / 128.0f) + LN_EPS);
; #pragma unroll
;       for (int d0 = 0; d0 < 4; ++d0) Ow[(long)orow * DM + d0 * 32 + r32_e] = (bf16)f2bf(v[d0] * rs * sw[d0]); }
	v_or_b32_e32 v245, 2, v30
	v_add_u32_e32 v244, v245, v8
	v_lshl_add_u32 v244, v244, 7, v138
	v_lshl_add_u32 v244, v244, 2, 0
	ds_read2_b32 v[236:237], v244 offset1:32
	ds_read2_b32 v[238:239], v244 offset0:64 offset1:96
	v_fma_f32 v9, -v160, v242, v93
	v_fmac_f32_e32 v95, v9, v9
	v_fma_f32 v93, -v160, v243, v94
	v_fmac_f32_e32 v95, v93, v93
	s_nop 1
	v_mov_b32_dpp v94, v95 quad_perm:[1,0,3,2] row_mask:0xf bank_mask:0xf
	v_add_f32_e32 v94, v95, v94
	s_nop 1
	v_mov_b32_dpp v95, v94 quad_perm:[2,3,0,1] row_mask:0xf bank_mask:0xf
	v_add_f32_e32 v94, v94, v95
	s_nop 1
	v_mov_b32_dpp v95, v94 row_half_mirror row_mask:0xf bank_mask:0xf
	v_add_f32_e32 v94, v94, v95
	s_nop 1
	v_mov_b32_dpp v95, v94 row_mirror row_mask:0xf bank_mask:0xf
	v_add_f32_e32 v94, v94, v95
	v_mov_b32_e32 v95, v94
	s_nop 1
	v_permlane16_swap_b32_e32 v94, v95
	v_add_f32_e32 v94, v94, v95
	v_fmamk_f32 v94, v94, 0x3c000000, v179
	v_cmp_gt_f32_e32 vcc, s4, v94
	v_mul_f32_e32 v95, 0x4f800000, v94
	s_nop 0
	v_cndmask_b32_e32 v94, v94, v95, vcc
	v_sqrt_f32_e32 v95, v94
	s_nop 0
	v_add_u32_e32 v96, -1, v95
	v_fma_f32 v97, -v96, v95, v94
	v_cmp_ge_f32_e64 s[0:1], 0, v97
	v_add_u32_e32 v97, 1, v95
	s_nop 0
	v_cndmask_b32_e64 v96, v95, v96, s[0:1]
	v_fma_f32 v95, -v97, v95, v94
	v_cmp_lt_f32_e64 s[0:1], 0, v95
	s_nop 1
	v_cndmask_b32_e64 v95, v96, v97, s[0:1]
	v_mul_f32_e32 v96, 0x37800000, v95
	v_cndmask_b32_e32 v95, v95, v96, vcc
	v_cmp_class_f32_e32 vcc, v94, v180
	s_nop 1
	v_cndmask_b32_e32 v94, v95, v94, vcc
	v_div_scale_f32 v95, s[0:1], v94, v94, 1.0
	v_rcp_f32_e32 v96, v95
	s_nop 0
	v_fma_f32 v97, -v95, v96, 1.0
	v_fmac_f32_e32 v96, v97, v96
	v_div_scale_f32 v97, vcc, 1.0, v94, 1.0
	v_mul_f32_e32 v99, v97, v96
	v_fma_f32 v100, -v95, v99, v97
	v_fmac_f32_e32 v99, v100, v96
	v_fma_f32 v95, -v95, v99, v97
	v_div_fmas_f32 v95, v95, v96, v99
	v_div_fixup_f32 v96, v95, v94, 1.0
	v_mul_f32_e32 v31, v31, v96
	v_ashrrev_i32_e32 v99, 31, v98
	v_mul_f32_e32 v31, v34, v31
	v_lshlrev_b64 v[94:95], 12, v[98:99]
	v_bfe_u32 v97, v31, 16, 1
	v_lshl_add_u64 v[94:95], v[4:5], 0, v[94:95]
	v_add3_u32 v31, v31, v97, s70
	global_store_short_d16_hi v[94:95], v31, off
	v_mul_f32_e32 v31, v88, v96
	v_mul_f32_e32 v31, v35, v31
	v_bfe_u32 v88, v31, 16, 1
	v_mul_f32_e32 v9, v9, v96
	v_add3_u32 v31, v31, v88, s70
	v_mul_f32_e32 v9, v36, v9
	global_store_short_d16_hi v[94:95], v31, off offset:64
	v_bfe_u32 v31, v9, 16, 1
	v_add3_u32 v9, v9, v31, s70
	global_store_short_d16_hi v[94:95], v9, off offset:128
	v_mul_f32_e32 v9, v93, v96
	v_mul_f32_e32 v9, v37, v9
	v_bfe_u32 v31, v9, 16, 1
	v_add3_u32 v9, v9, v31, s70
	v_or_b32_e32 v88, 2, v30
	global_store_short_d16_hi v[94:95], v9, off offset:192
	v_add_u32_e32 v9, v88, v8
	v_lshl_add_u32 v9, v9, 7, v138
	v_lshl_add_u32 v9, v9, 2, 0
	v_or_b32_e32 v30, 3, v30
	s_waitcnt lgkmcnt(1)
	v_fma_f32 v31, -v160, v236, v91
	v_fma_f32 v91, -v160, v237, v92
	v_mul_f32_e32 v94, v91, v91
	v_fmac_f32_e32 v94, v31, v31
	s_waitcnt lgkmcnt(0)
	v_add_u32_e32 v244, v30, v8
	v_lshl_add_u32 v244, v244, 7, v138
	v_lshl_add_u32 v244, v244, 2, 0
	ds_read2_b32 v[240:241], v244 offset1:32
	ds_read2_b32 v[242:243], v244 offset0:64 offset1:96
	v_fma_f32 v9, -v160, v238, v89
	v_fmac_f32_e32 v94, v9, v9
	v_fma_f32 v90, -v160, v239, v90
	v_fmac_f32_e32 v94, v90, v90
	s_nop 1
	v_mov_b32_dpp v89, v94 quad_perm:[1,0,3,2] row_mask:0xf bank_mask:0xf
	v_add_f32_e32 v89, v94, v89
	s_nop 1
	v_mov_b32_dpp v92, v89 quad_perm:[2,3,0,1] row_mask:0xf bank_mask:0xf
	v_add_f32_e32 v89, v89, v92
	s_nop 1
	v_mov_b32_dpp v92, v89 row_half_mirror row_mask:0xf bank_mask:0xf
	v_add_f32_e32 v89, v89, v92
	s_nop 1
	v_mov_b32_dpp v92, v89 row_mirror row_mask:0xf bank_mask:0xf
	v_add_f32_e32 v89, v89, v92
	v_mov_b32_e32 v92, v89
	s_nop 1
	v_permlane16_swap_b32_e32 v89, v92
	v_add_f32_e32 v89, v89, v92
	v_fmamk_f32 v89, v89, 0x3c000000, v179
	v_cmp_gt_f32_e32 vcc, s4, v89
	v_mul_f32_e32 v92, 0x4f800000, v89
	s_nop 0
	v_cndmask_b32_e32 v89, v89, v92, vcc
	v_sqrt_f32_e32 v92, v89
	s_nop 0
	v_add_u32_e32 v93, -1, v92
	v_fma_f32 v94, -v93, v92, v89
	v_cmp_ge_f32_e64 s[0:1], 0, v94
	v_add_u32_e32 v94, 1, v92
	s_nop 0
	v_cndmask_b32_e64 v93, v92, v93, s[0:1]
	v_fma_f32 v92, -v94, v92, v89
	v_cmp_lt_f32_e64 s[0:1], 0, v92
	s_nop 1
	v_cndmask_b32_e64 v92, v93, v94, s[0:1]
	v_mul_f32_e32 v93, 0x37800000, v92
	v_cndmask_b32_e32 v92, v92, v93, vcc
	v_cmp_class_f32_e32 vcc, v89, v180
	s_nop 1
	v_cndmask_b32_e32 v89, v92, v89, vcc
	v_div_scale_f32 v92, s[0:1], v89, v89, 1.0
	v_rcp_f32_e32 v93, v92
	s_nop 0
	v_fma_f32 v94, -v92, v93, 1.0
	v_fmac_f32_e32 v93, v94, v93
	v_div_scale_f32 v94, vcc, 1.0, v89, 1.0
	v_mul_f32_e32 v95, v94, v93
	v_fma_f32 v96, -v92, v95, v94
	v_fmac_f32_e32 v95, v96, v93
	v_fma_f32 v92, -v92, v95, v94
	v_div_fmas_f32 v92, v92, v93, v95
	v_div_fixup_f32 v92, v92, v89, 1.0
	v_mul_f32_e32 v31, v31, v92
	v_ashrrev_i32_e32 v89, 31, v88
	v_mul_f32_e32 v31, v34, v31
	v_lshlrev_b64 v[88:89], 12, v[88:89]
	v_bfe_u32 v93, v31, 16, 1
	v_lshl_add_u64 v[88:89], v[4:5], 0, v[88:89]
	v_add3_u32 v31, v31, v93, s70
	global_store_short_d16_hi v[88:89], v31, off
	v_mul_f32_e32 v31, v91, v92
	v_mul_f32_e32 v31, v35, v31
	v_bfe_u32 v91, v31, 16, 1
	v_mul_f32_e32 v9, v9, v92
	v_add3_u32 v31, v31, v91, s70
	v_mul_f32_e32 v9, v36, v9
	global_store_short_d16_hi v[88:89], v31, off offset:64
	v_bfe_u32 v31, v9, 16, 1
	v_add3_u32 v9, v9, v31, s70
	global_store_short_d16_hi v[88:89], v9, off offset:128
	v_mul_f32_e32 v9, v90, v92
	v_mul_f32_e32 v9, v37, v9
	v_bfe_u32 v31, v9, 16, 1
	v_add3_u32 v9, v9, v31, s70
	global_store_short_d16_hi v[88:89], v9, off offset:192
	v_add_u32_e32 v9, v30, v8
	v_lshl_add_u32 v9, v9, 7, v138
	v_lshl_add_u32 v9, v9, 2, 0
	s_waitcnt lgkmcnt(1)
; __device__ __forceinline__ unsigned f2bf(float f) { unsigned u = __builtin_bit_cast(unsigned, f); return (u + 0x7fffu + ((u >> 16) & 1u)) >> 16; }
; __device__ __forceinline__ int crow(int r, int hi) { return (r & 3) + 8 * (r >> 2) + 4 * hi; }
; __device__ __forceinline__ void attn_unit(const bf16* __restrict__ Qb, const bf16* __restrict__ Kh, const bf16* __restrict__ Vh, int klat0, int nlt, int kctx0, int NT,
;                                           float lam, float post, const float* __restrict__ subw, bf16* __restrict__ Ob, char* lds) {
;     ...
;     for (int r = 0; r < 16; ++r) { const int orow = crow(r, hi_e); float v[4]; float ss = 0.f;
; #pragma unroll
;       for (int d0 = 0; d0 < 4; ++d0) { v[d0] = o[d0][r] - lam * X[(wq_e * 32 + orow) * 128 + d0 * 32 + r32_e]; ss += v[d0] * v[d0]; }
;       ss += __shfl_xor(ss, 1); ss += __shfl_xor(ss, 2); ss += __shfl_xor(ss, 4); ss += __shfl_xor(ss, 8); ss += __shfl_xor(ss, 16);
;       const float rs = 1.0f / sqrtf(ss * (1.0f / 128.0f) + LN_EPS);
; #pragma unroll
;       for (int d0 = 0; d0 < 4; ++d0) Ow[(long)orow * DM + d0 * 32 + r32_e] = (bf16)f2bf(v[d0] * rs * sw[d0]); }
	v_fma_f32 v88, -v160, v240, v86
	v_fma_f32 v89, -v160, v241, v87
	v_mul_f32_e32 v31, v89, v89
	v_fmac_f32_e32 v31, v88, v88
	s_waitcnt lgkmcnt(0)
	v_add_u32_e32 v244, v28, v8
	v_lshl_add_u32 v244, v244, 7, v138
	v_lshl_add_u32 v244, v244, 2, 0
	ds_read2_b32 v[236:237], v244 offset1:32
	ds_read2_b32 v[238:239], v244 offset0:64 offset1:96
	v_fma_f32 v9, -v160, v242, v84
	v_fmac_f32_e32 v31, v9, v9
	v_fma_f32 v84, -v160, v243, v85
	v_fmac_f32_e32 v31, v84, v84
	s_nop 1
	v_mov_b32_dpp v85, v31 quad_perm:[1,0,3,2] row_mask:0xf bank_mask:0xf
	v_add_f32_e32 v31, v31, v85
	s_nop 1
	v_mov_b32_dpp v85, v31 quad_perm:[2,3,0,1] row_mask:0xf bank_mask:0xf
	v_add_f32_e32 v31, v31, v85
	s_nop 1
	v_mov_b32_dpp v85, v31 row_half_mirror row_mask:0xf bank_mask:0xf
	v_add_f32_e32 v31, v31, v85
	s_nop 1
	v_mov_b32_dpp v85, v31 row_mirror row_mask:0xf bank_mask:0xf
	v_add_f32_e32 v31, v31, v85
	v_mov_b32_e32 v85, v31
	s_nop 1
	v_permlane16_swap_b32_e32 v31, v85
	v_add_f32_e32 v31, v31, v85
	v_fmamk_f32 v31, v31, 0x3c000000, v179
	v_cmp_gt_f32_e32 vcc, s4, v31
	v_mul_f32_e32 v85, 0x4f800000, v31
	s_nop 0
	v_cndmask_b32_e32 v31, v31, v85, vcc
	v_sqrt_f32_e32 v85, v31
	s_nop 0
	v_add_u32_e32 v86, -1, v85
	v_fma_f32 v87, -v86, v85, v31
	v_cmp_ge_f32_e64 s[0:1], 0, v87
	v_add_u32_e32 v87, 1, v85
	s_nop 0
	v_cndmask_b32_e64 v86, v85, v86, s[0:1]
	v_fma_f32 v85, -v87, v85, v31
	v_cmp_lt_f32_e64 s[0:1], 0, v85
	s_nop 1
	v_cndmask_b32_e64 v85, v86, v87, s[0:1]
	v_mul_f32_e32 v86, 0x37800000, v85
	v_cndmask_b32_e32 v85, v85, v86, vcc
	v_cmp_class_f32_e32 vcc, v31, v180
	s_nop 1
	v_cndmask_b32_e32 v31, v85, v31, vcc
	v_div_scale_f32 v85, s[0:1], v31, v31, 1.0
	v_rcp_f32_e32 v86, v85
	s_nop 0
	v_fma_f32 v87, -v85, v86, 1.0
	v_fmac_f32_e32 v86, v87, v86
	v_div_scale_f32 v87, vcc, 1.0, v31, 1.0
	v_mul_f32_e32 v90, v87, v86
	v_fma_f32 v91, -v85, v90, v87
	v_fmac_f32_e32 v90, v91, v86
	v_fma_f32 v85, -v85, v90, v87
	v_div_fmas_f32 v85, v85, v86, v90
	v_div_fixup_f32 v85, v85, v31, 1.0
	v_mul_f32_e32 v86, v88, v85
	v_ashrrev_i32_e32 v31, 31, v30
	v_mul_f32_e32 v86, v34, v86
	v_lshlrev_b64 v[30:31], 12, v[30:31]
	v_bfe_u32 v87, v86, 16, 1
	v_lshl_add_u64 v[30:31], v[4:5], 0, v[30:31]
	v_add3_u32 v86, v86, v87, s70
	global_store_short_d16_hi v[30:31], v86, off
	v_mul_f32_e32 v86, v89, v85
	v_mul_f32_e32 v86, v35, v86
	v_bfe_u32 v87, v86, 16, 1
	v_mul_f32_e32 v9, v9, v85
	v_add3_u32 v86, v86, v87, s70
	v_mul_f32_e32 v9, v36, v9
	global_store_short_d16_hi v[30:31], v86, off offset:64
	v_bfe_u32 v86, v9, 16, 1
	v_add3_u32 v9, v9, v86, s70
	global_store_short_d16_hi v[30:31], v9, off offset:128
	v_mul_f32_e32 v9, v84, v85
	v_mul_f32_e32 v9, v37, v9
	v_bfe_u32 v84, v9, 16, 1
	v_add3_u32 v9, v9, v84, s70
	global_store_short_d16_hi v[30:31], v9, off offset:192
	v_add_u32_e32 v9, v28, v8
	v_lshl_add_u32 v9, v9, 7, v138
	v_lshl_add_u32 v9, v9, 2, 0
	v_lshlrev_b64 v[28:29], 12, v[28:29]
	v_lshl_add_u64 v[28:29], v[4:5], 0, v[28:29]
	s_waitcnt lgkmcnt(1)
	v_fma_f32 v82, -v160, v236, v82
	v_fma_f32 v83, -v160, v237, v83
	v_mul_f32_e32 v84, v83, v83
	v_fmac_f32_e32 v84, v82, v82
	s_waitcnt lgkmcnt(0)
	v_add_u32_e32 v244, v26, v8
	v_lshl_add_u32 v244, v244, 7, v138
	v_lshl_add_u32 v244, v244, 2, 0
	ds_read2_b32 v[240:241], v244 offset1:32
	ds_read2_b32 v[242:243], v244 offset0:64 offset1:96
	v_fma_f32 v9, -v160, v238, v65
	v_fmac_f32_e32 v84, v9, v9
	v_fma_f32 v30, -v160, v239, v81
	v_fmac_f32_e32 v84, v30, v30
	s_nop 1
	v_mov_b32_dpp v31, v84 quad_perm:[1,0,3,2] row_mask:0xf bank_mask:0xf
	v_add_f32_e32 v31, v84, v31
	s_nop 1
	v_mov_b32_dpp v65, v31 quad_perm:[2,3,0,1] row_mask:0xf bank_mask:0xf
	v_add_f32_e32 v31, v31, v65
	s_nop 1
	v_mov_b32_dpp v65, v31 row_half_mirror row_mask:0xf bank_mask:0xf
	v_add_f32_e32 v31, v31, v65
	s_nop 1
	v_mov_b32_dpp v65, v31 row_mirror row_mask:0xf bank_mask:0xf
	v_add_f32_e32 v31, v31, v65
	v_mov_b32_e32 v65, v31
	s_nop 1
	v_permlane16_swap_b32_e32 v31, v65
	v_add_f32_e32 v31, v31, v65
	v_fmamk_f32 v31, v31, 0x3c000000, v179
	v_cmp_gt_f32_e32 vcc, s4, v31
	v_mul_f32_e32 v65, 0x4f800000, v31
	s_nop 0
	v_cndmask_b32_e32 v31, v31, v65, vcc
	v_sqrt_f32_e32 v65, v31
	s_nop 0
	v_add_u32_e32 v81, -1, v65
	v_fma_f32 v84, -v81, v65, v31
	v_cmp_ge_f32_e64 s[0:1], 0, v84
	v_add_u32_e32 v84, 1, v65
	s_nop 0
	v_cndmask_b32_e64 v81, v65, v81, s[0:1]
	v_fma_f32 v65, -v84, v65, v31
	v_cmp_lt_f32_e64 s[0:1], 0, v65
	s_nop 1
	v_cndmask_b32_e64 v65, v81, v84, s[0:1]
	v_mul_f32_e32 v81, 0x37800000, v65
	v_cndmask_b32_e32 v65, v65, v81, vcc
	v_cmp_class_f32_e32 vcc, v31, v180
	s_nop 1
	v_cndmask_b32_e32 v31, v65, v31, vcc
	v_div_scale_f32 v65, s[0:1], v31, v31, 1.0
	v_rcp_f32_e32 v81, v65
	s_nop 0
	v_fma_f32 v84, -v65, v81, 1.0
	v_fmac_f32_e32 v81, v84, v81
	v_div_scale_f32 v84, vcc, 1.0, v31, 1.0
	v_mul_f32_e32 v85, v84, v81
	v_fma_f32 v86, -v65, v85, v84
	v_fmac_f32_e32 v85, v86, v81
	v_fma_f32 v65, -v65, v85, v84
	v_div_fmas_f32 v65, v65, v81, v85
	v_div_fixup_f32 v31, v65, v31, 1.0
	v_mul_f32_e32 v65, v82, v31
	v_mul_f32_e32 v65, v34, v65
	v_bfe_u32 v81, v65, 16, 1
	v_add3_u32 v65, v65, v81, s70
	global_store_short_d16_hi v[28:29], v65, off
	v_mul_f32_e32 v65, v83, v31
	v_mul_f32_e32 v65, v35, v65
	v_bfe_u32 v81, v65, 16, 1
	v_mul_f32_e32 v9, v9, v31
	v_add3_u32 v65, v65, v81, s70
	v_mul_f32_e32 v9, v36, v9
	global_store_short_d16_hi v[28:29], v65, off offset:64
	v_bfe_u32 v65, v9, 16, 1
	v_add3_u32 v9, v9, v65, s70
	global_store_short_d16_hi v[28:29], v9, off offset:128
	v_mul_f32_e32 v9, v30, v31
	v_mul_f32_e32 v9, v37, v9
	v_bfe_u32 v30, v9, 16, 1
	v_add3_u32 v9, v9, v30, s70
	global_store_short_d16_hi v[28:29], v9, off offset:192
	v_add_u32_e32 v9, v26, v8
	v_lshl_add_u32 v9, v9, 7, v138
	v_lshl_add_u32 v9, v9, 2, 0
	v_lshlrev_b64 v[26:27], 12, v[26:27]
	v_lshl_add_u64 v[26:27], v[4:5], 0, v[26:27]
	s_waitcnt lgkmcnt(1)
; __device__ __forceinline__ unsigned f2bf(float f) { unsigned u = __builtin_bit_cast(unsigned, f); return (u + 0x7fffu + ((u >> 16) & 1u)) >> 16; }
; __device__ __forceinline__ int crow(int r, int hi) { return (r & 3) + 8 * (r >> 2) + 4 * hi; }
; __device__ __forceinline__ void attn_unit(const bf16* __restrict__ Qb, const bf16* __restrict__ Kh, const bf16* __restrict__ Vh, int klat0, int nlt, int kctx0, int NT,
;                                           float lam, float post, const float* __restrict__ subw, bf16* __restrict__ Ob, char* lds) {
;     ...
;     for (int r = 0; r < 16; ++r) { const int orow = crow(r, hi_e); float v[4]; float ss = 0.f;
; #pragma unroll
;       for (int d0 = 0; d0 < 4; ++d0) { v[d0] = o[d0][r] - lam * X[(wq_e * 32 + orow) * 128 + d0 * 32 + r32_e]; ss += v[d0] * v[d0]; }
;       ss += __shfl_xor(ss, 1); ss += __shfl_xor(ss, 2); ss += __shfl_xor(ss, 4); ss += __shfl_xor(ss, 8); ss += __shfl_xor(ss, 16);
;       const float rs = 1.0f / sqrtf(ss * (1.0f / 128.0f) + LN_EPS);
; #pragma unroll
;       for (int d0 = 0; d0 < 4; ++d0) Ow[(long)orow * DM + d0 * 32 + r32_e] = (bf16)f2bf(v[d0] * rs * sw[d0]); }
	v_fma_f32 v30, -v160, v240, v79
	v_fma_f32 v31, -v160, v241, v80
	v_mul_f32_e32 v65, v31, v31
	v_fmac_f32_e32 v65, v30, v30
	s_waitcnt lgkmcnt(0)
	v_add_u32_e32 v244, v24, v8
	v_lshl_add_u32 v244, v244, 7, v138
	v_lshl_add_u32 v244, v244, 2, 0
	ds_read2_b32 v[236:237], v244 offset1:32
	ds_read2_b32 v[238:239], v244 offset0:64 offset1:96
	v_fma_f32 v9, -v160, v242, v63
	v_fmac_f32_e32 v65, v9, v9
	v_fma_f32 v28, -v160, v243, v64
	v_fmac_f32_e32 v65, v28, v28
	s_nop 1
	v_mov_b32_dpp v29, v65 quad_perm:[1,0,3,2] row_mask:0xf bank_mask:0xf
	v_add_f32_e32 v29, v65, v29
	s_nop 1
	v_mov_b32_dpp v63, v29 quad_perm:[2,3,0,1] row_mask:0xf bank_mask:0xf
	v_add_f32_e32 v29, v29, v63
	s_nop 1
	v_mov_b32_dpp v63, v29 row_half_mirror row_mask:0xf bank_mask:0xf
	v_add_f32_e32 v29, v29, v63
	s_nop 1
	v_mov_b32_dpp v63, v29 row_mirror row_mask:0xf bank_mask:0xf
	v_add_f32_e32 v29, v29, v63
	v_mov_b32_e32 v63, v29
	s_nop 1
	v_permlane16_swap_b32_e32 v29, v63
	v_add_f32_e32 v29, v29, v63
	v_fmamk_f32 v29, v29, 0x3c000000, v179
	v_cmp_gt_f32_e32 vcc, s4, v29
	v_mul_f32_e32 v63, 0x4f800000, v29
	s_nop 0
	v_cndmask_b32_e32 v29, v29, v63, vcc
	v_sqrt_f32_e32 v63, v29
	s_nop 0
	v_add_u32_e32 v64, -1, v63
	v_fma_f32 v65, -v64, v63, v29
	v_cmp_ge_f32_e64 s[0:1], 0, v65
	v_add_u32_e32 v65, 1, v63
	s_nop 0
	v_cndmask_b32_e64 v64, v63, v64, s[0:1]
	v_fma_f32 v63, -v65, v63, v29
	v_cmp_lt_f32_e64 s[0:1], 0, v63
	s_nop 1
	v_cndmask_b32_e64 v63, v64, v65, s[0:1]
	v_mul_f32_e32 v64, 0x37800000, v63
	v_cndmask_b32_e32 v63, v63, v64, vcc
	v_cmp_class_f32_e32 vcc, v29, v180
	s_nop 1
	v_cndmask_b32_e32 v29, v63, v29, vcc
	v_div_scale_f32 v63, s[0:1], v29, v29, 1.0
	v_rcp_f32_e32 v64, v63
	s_nop 0
	v_fma_f32 v65, -v63, v64, 1.0
	v_fmac_f32_e32 v64, v65, v64
	v_div_scale_f32 v65, vcc, 1.0, v29, 1.0
	v_mul_f32_e32 v79, v65, v64
	v_fma_f32 v80, -v63, v79, v65
	v_fmac_f32_e32 v79, v80, v64
	v_fma_f32 v63, -v63, v79, v65
	v_div_fmas_f32 v63, v63, v64, v79
	v_div_fixup_f32 v29, v63, v29, 1.0
	v_mul_f32_e32 v30, v30, v29
	v_mul_f32_e32 v30, v34, v30
	v_bfe_u32 v63, v30, 16, 1
	v_add3_u32 v30, v30, v63, s70
	global_store_short_d16_hi v[26:27], v30, off
	v_mul_f32_e32 v30, v31, v29
	v_mul_f32_e32 v30, v35, v30
	v_bfe_u32 v31, v30, 16, 1
	v_mul_f32_e32 v9, v9, v29
	v_add3_u32 v30, v30, v31, s70
	v_mul_f32_e32 v9, v36, v9
	global_store_short_d16_hi v[26:27], v30, off offset:64
	v_bfe_u32 v30, v9, 16, 1
	v_add3_u32 v9, v9, v30, s70
	global_store_short_d16_hi v[26:27], v9, off offset:128
	v_mul_f32_e32 v9, v28, v29
	v_mul_f32_e32 v9, v37, v9
	v_bfe_u32 v28, v9, 16, 1
	v_add3_u32 v9, v9, v28, s70
	global_store_short_d16_hi v[26:27], v9, off offset:192
	v_add_u32_e32 v9, v24, v8
	v_lshl_add_u32 v9, v9, 7, v138
	v_lshl_add_u32 v9, v9, 2, 0
	v_lshlrev_b64 v[24:25], 12, v[24:25]
	v_lshl_add_u64 v[24:25], v[4:5], 0, v[24:25]
	s_waitcnt lgkmcnt(1)
	v_fma_f32 v28, -v160, v236, v77
	v_fma_f32 v29, -v160, v237, v78
	v_mul_f32_e32 v30, v29, v29
	v_fmac_f32_e32 v30, v28, v28
	s_waitcnt lgkmcnt(0)
	v_add_u32_e32 v244, v22, v8
	v_lshl_add_u32 v244, v244, 7, v138
	v_lshl_add_u32 v244, v244, 2, 0
	ds_read2_b32 v[240:241], v244 offset1:32
	ds_read2_b32 v[242:243], v244 offset0:64 offset1:96
	v_fma_f32 v9, -v160, v238, v61
	v_fmac_f32_e32 v30, v9, v9
	v_fma_f32 v26, -v160, v239, v62
	v_fmac_f32_e32 v30, v26, v26
	s_nop 1
	v_mov_b32_dpp v27, v30 quad_perm:[1,0,3,2] row_mask:0xf bank_mask:0xf
	v_add_f32_e32 v27, v30, v27
	s_nop 1
	v_mov_b32_dpp v30, v27 quad_perm:[2,3,0,1] row_mask:0xf bank_mask:0xf
	v_add_f32_e32 v27, v27, v30
	s_nop 1
	v_mov_b32_dpp v30, v27 row_half_mirror row_mask:0xf bank_mask:0xf
	v_add_f32_e32 v27, v27, v30
	s_nop 1
	v_mov_b32_dpp v30, v27 row_mirror row_mask:0xf bank_mask:0xf
	v_add_f32_e32 v27, v27, v30
	v_mov_b32_e32 v30, v27
	s_nop 1
	v_permlane16_swap_b32_e32 v27, v30
	v_add_f32_e32 v27, v27, v30
	v_fmamk_f32 v27, v27, 0x3c000000, v179
	v_cmp_gt_f32_e32 vcc, s4, v27
	v_mul_f32_e32 v30, 0x4f800000, v27
	s_nop 0
	v_cndmask_b32_e32 v27, v27, v30, vcc
	v_sqrt_f32_e32 v30, v27
	s_nop 0
	v_add_u32_e32 v31, -1, v30
	v_fma_f32 v61, -v31, v30, v27
	v_cmp_ge_f32_e64 s[0:1], 0, v61
	v_add_u32_e32 v61, 1, v30
	s_nop 0
	v_cndmask_b32_e64 v31, v30, v31, s[0:1]
	v_fma_f32 v30, -v61, v30, v27
	v_cmp_lt_f32_e64 s[0:1], 0, v30
	s_nop 1
	v_cndmask_b32_e64 v30, v31, v61, s[0:1]
	v_mul_f32_e32 v31, 0x37800000, v30
	v_cndmask_b32_e32 v30, v30, v31, vcc
	v_cmp_class_f32_e32 vcc, v27, v180
	s_nop 1
	v_cndmask_b32_e32 v27, v30, v27, vcc
	v_div_scale_f32 v30, s[0:1], v27, v27, 1.0
	v_rcp_f32_e32 v31, v30
	s_nop 0
	v_fma_f32 v61, -v30, v31, 1.0
	v_fmac_f32_e32 v31, v61, v31
	v_div_scale_f32 v61, vcc, 1.0, v27, 1.0
	v_mul_f32_e32 v62, v61, v31
	v_fma_f32 v63, -v30, v62, v61
	v_fmac_f32_e32 v62, v63, v31
	v_fma_f32 v30, -v30, v62, v61
	v_div_fmas_f32 v30, v30, v31, v62
	v_div_fixup_f32 v27, v30, v27, 1.0
	v_mul_f32_e32 v28, v28, v27
	v_mul_f32_e32 v28, v34, v28
	v_bfe_u32 v30, v28, 16, 1
	v_add3_u32 v28, v28, v30, s70
	global_store_short_d16_hi v[24:25], v28, off
	v_mul_f32_e32 v28, v29, v27
	v_mul_f32_e32 v28, v35, v28
	v_bfe_u32 v29, v28, 16, 1
	v_mul_f32_e32 v9, v9, v27
	v_add3_u32 v28, v28, v29, s70
	v_mul_f32_e32 v9, v36, v9
	global_store_short_d16_hi v[24:25], v28, off offset:64
	v_bfe_u32 v28, v9, 16, 1
	v_add3_u32 v9, v9, v28, s70
	global_store_short_d16_hi v[24:25], v9, off offset:128
	v_mul_f32_e32 v9, v26, v27
	v_mul_f32_e32 v9, v37, v9
	v_bfe_u32 v26, v9, 16, 1
	v_add3_u32 v9, v9, v26, s70
	global_store_short_d16_hi v[24:25], v9, off offset:192
	v_add_u32_e32 v9, v22, v8
	v_lshl_add_u32 v9, v9, 7, v138
	v_lshl_add_u32 v9, v9, 2, 0
	v_lshlrev_b64 v[22:23], 12, v[22:23]
	v_lshl_add_u64 v[22:23], v[4:5], 0, v[22:23]
	s_waitcnt lgkmcnt(1)
; __device__ __forceinline__ unsigned f2bf(float f) { unsigned u = __builtin_bit_cast(unsigned, f); return (u + 0x7fffu + ((u >> 16) & 1u)) >> 16; }
; __device__ __forceinline__ int crow(int r, int hi) { return (r & 3) + 8 * (r >> 2) + 4 * hi; }
; __device__ __forceinline__ void attn_unit(const bf16* __restrict__ Qb, const bf16* __restrict__ Kh, const bf16* __restrict__ Vh, int klat0, int nlt, int kctx0, int NT,
;                                           float lam, float post, const float* __restrict__ subw, bf16* __restrict__ Ob, char* lds) {
;     ...
;     for (int r = 0; r < 16; ++r) { const int orow = crow(r, hi_e); float v[4]; float ss = 0.f;
; #pragma unroll
;       for (int d0 = 0; d0 < 4; ++d0) { v[d0] = o[d0][r] - lam * X[(wq_e * 32 + orow) * 128 + d0 * 32 + r32_e]; ss += v[d0] * v[d0]; }
;       ss += __shfl_xor(ss, 1); ss += __shfl_xor(ss, 2); ss += __shfl_xor(ss, 4); ss += __shfl_xor(ss, 8); ss += __shfl_xor(ss, 16);
;       const float rs = 1.0f / sqrtf(ss * (1.0f / 128.0f) + LN_EPS);
; #pragma unroll
;       for (int d0 = 0; d0 < 4; ++d0) Ow[(long)orow * DM + d0 * 32 + r32_e] = (bf16)f2bf(v[d0] * rs * sw[d0]); }
	v_fma_f32 v26, -v160, v240, v75
	v_fma_f32 v27, -v160, v241, v76
	v_mul_f32_e32 v28, v27, v27
	v_fmac_f32_e32 v28, v26, v26
	s_waitcnt lgkmcnt(0)
	v_add_u32_e32 v244, v20, v8
	v_lshl_add_u32 v244, v244, 7, v138
	v_lshl_add_u32 v244, v244, 2, 0
	ds_read2_b32 v[236:237], v244 offset1:32
	ds_read2_b32 v[238:239], v244 offset0:64 offset1:96
	v_fma_f32 v9, -v160, v242, v60
	v_fmac_f32_e32 v28, v9, v9
	v_fma_f32 v24, -v160, v243, v49
	v_fmac_f32_e32 v28, v24, v24
	s_nop 1
	v_mov_b32_dpp v25, v28 quad_perm:[1,0,3,2] row_mask:0xf bank_mask:0xf
	v_add_f32_e32 v25, v28, v25
	s_nop 1
	v_mov_b32_dpp v28, v25 quad_perm:[2,3,0,1] row_mask:0xf bank_mask:0xf
	v_add_f32_e32 v25, v25, v28
	s_nop 1
	v_mov_b32_dpp v28, v25 row_half_mirror row_mask:0xf bank_mask:0xf
	v_add_f32_e32 v25, v25, v28
	s_nop 1
	v_mov_b32_dpp v28, v25 row_mirror row_mask:0xf bank_mask:0xf
	v_add_f32_e32 v25, v25, v28
	v_mov_b32_e32 v28, v25
	s_nop 1
	v_permlane16_swap_b32_e32 v25, v28
	v_add_f32_e32 v25, v25, v28
	v_fmamk_f32 v25, v25, 0x3c000000, v179
	v_cmp_gt_f32_e32 vcc, s4, v25
	v_mul_f32_e32 v28, 0x4f800000, v25
	s_nop 0
	v_cndmask_b32_e32 v25, v25, v28, vcc
	v_sqrt_f32_e32 v28, v25
	s_nop 0
	v_add_u32_e32 v29, -1, v28
	v_fma_f32 v30, -v29, v28, v25
	v_cmp_ge_f32_e64 s[0:1], 0, v30
	v_add_u32_e32 v30, 1, v28
	s_nop 0
	v_cndmask_b32_e64 v29, v28, v29, s[0:1]
	v_fma_f32 v28, -v30, v28, v25
	v_cmp_lt_f32_e64 s[0:1], 0, v28
	s_nop 1
	v_cndmask_b32_e64 v28, v29, v30, s[0:1]
	v_mul_f32_e32 v29, 0x37800000, v28
	v_cndmask_b32_e32 v28, v28, v29, vcc
	v_cmp_class_f32_e32 vcc, v25, v180
	s_nop 1
	v_cndmask_b32_e32 v25, v28, v25, vcc
	v_div_scale_f32 v28, s[0:1], v25, v25, 1.0
	v_rcp_f32_e32 v29, v28
	s_nop 0
	v_fma_f32 v30, -v28, v29, 1.0
	v_fmac_f32_e32 v29, v30, v29
	v_div_scale_f32 v30, vcc, 1.0, v25, 1.0
	v_mul_f32_e32 v31, v30, v29
	v_fma_f32 v49, -v28, v31, v30
	v_fmac_f32_e32 v31, v49, v29
	v_fma_f32 v28, -v28, v31, v30
	v_div_fmas_f32 v28, v28, v29, v31
	v_div_fixup_f32 v25, v28, v25, 1.0
	v_mul_f32_e32 v26, v26, v25
	v_mul_f32_e32 v26, v34, v26
	v_bfe_u32 v28, v26, 16, 1
	v_add3_u32 v26, v26, v28, s70
	global_store_short_d16_hi v[22:23], v26, off
	v_mul_f32_e32 v26, v27, v25
	v_mul_f32_e32 v26, v35, v26
	v_bfe_u32 v27, v26, 16, 1
	v_mul_f32_e32 v9, v9, v25
	v_add3_u32 v26, v26, v27, s70
	v_mul_f32_e32 v9, v36, v9
	global_store_short_d16_hi v[22:23], v26, off offset:64
	v_bfe_u32 v26, v9, 16, 1
	v_add3_u32 v9, v9, v26, s70
	global_store_short_d16_hi v[22:23], v9, off offset:128
	v_mul_f32_e32 v9, v24, v25
	v_mul_f32_e32 v9, v37, v9
	v_bfe_u32 v24, v9, 16, 1
	v_add3_u32 v9, v9, v24, s70
	global_store_short_d16_hi v[22:23], v9, off offset:192
	v_add_u32_e32 v9, v20, v8
	v_lshl_add_u32 v9, v9, 7, v138
	v_lshl_add_u32 v9, v9, 2, 0
	v_lshlrev_b64 v[20:21], 12, v[20:21]
	v_lshl_add_u64 v[20:21], v[4:5], 0, v[20:21]
	s_waitcnt lgkmcnt(1)
	v_fma_f32 v24, -v160, v236, v73
	v_fma_f32 v25, -v160, v237, v74
	v_mul_f32_e32 v26, v25, v25
	v_fmac_f32_e32 v26, v24, v24
	s_waitcnt lgkmcnt(0)
	v_add_u32_e32 v244, v18, v8
	v_lshl_add_u32 v244, v244, 7, v138
	v_lshl_add_u32 v244, v244, 2, 0
	ds_read2_b32 v[240:241], v244 offset1:32
	ds_read2_b32 v[242:243], v244 offset0:64 offset1:96
	v_fma_f32 v9, -v160, v238, v59
	v_fmac_f32_e32 v26, v9, v9
	v_fma_f32 v22, -v160, v239, v48
	v_fmac_f32_e32 v26, v22, v22
	s_nop 1
	v_mov_b32_dpp v23, v26 quad_perm:[1,0,3,2] row_mask:0xf bank_mask:0xf
	v_add_f32_e32 v23, v26, v23
	s_nop 1
	v_mov_b32_dpp v26, v23 quad_perm:[2,3,0,1] row_mask:0xf bank_mask:0xf
	v_add_f32_e32 v23, v23, v26
	s_nop 1
	v_mov_b32_dpp v26, v23 row_half_mirror row_mask:0xf bank_mask:0xf
	v_add_f32_e32 v23, v23, v26
	s_nop 1
	v_mov_b32_dpp v26, v23 row_mirror row_mask:0xf bank_mask:0xf
	v_add_f32_e32 v23, v23, v26
	v_mov_b32_e32 v26, v23
	s_nop 1
	v_permlane16_swap_b32_e32 v23, v26
	v_add_f32_e32 v23, v23, v26
	v_fmamk_f32 v23, v23, 0x3c000000, v179
	v_cmp_gt_f32_e32 vcc, s4, v23
	v_mul_f32_e32 v26, 0x4f800000, v23
	s_nop 0
	v_cndmask_b32_e32 v23, v23, v26, vcc
	v_sqrt_f32_e32 v26, v23
	s_nop 0
	v_add_u32_e32 v27, -1, v26
	v_fma_f32 v28, -v27, v26, v23
	v_cmp_ge_f32_e64 s[0:1], 0, v28
	v_add_u32_e32 v28, 1, v26
	s_nop 0
	v_cndmask_b32_e64 v27, v26, v27, s[0:1]
	v_fma_f32 v26, -v28, v26, v23
	v_cmp_lt_f32_e64 s[0:1], 0, v26
	s_nop 1
	v_cndmask_b32_e64 v26, v27, v28, s[0:1]
	v_mul_f32_e32 v27, 0x37800000, v26
	v_cndmask_b32_e32 v26, v26, v27, vcc
	v_cmp_class_f32_e32 vcc, v23, v180
	s_nop 1
	v_cndmask_b32_e32 v23, v26, v23, vcc
	v_div_scale_f32 v26, s[0:1], v23, v23, 1.0
	v_rcp_f32_e32 v27, v26
	s_nop 0
	v_fma_f32 v28, -v26, v27, 1.0
	v_fmac_f32_e32 v27, v28, v27
	v_div_scale_f32 v28, vcc, 1.0, v23, 1.0
	v_mul_f32_e32 v29, v28, v27
	v_fma_f32 v30, -v26, v29, v28
	v_fmac_f32_e32 v29, v30, v27
	v_fma_f32 v26, -v26, v29, v28
	v_div_fmas_f32 v26, v26, v27, v29
	v_div_fixup_f32 v23, v26, v23, 1.0
	v_mul_f32_e32 v24, v24, v23
	v_mul_f32_e32 v24, v34, v24
	v_bfe_u32 v26, v24, 16, 1
	v_add3_u32 v24, v24, v26, s70
	global_store_short_d16_hi v[20:21], v24, off
	v_mul_f32_e32 v24, v25, v23
	v_mul_f32_e32 v24, v35, v24
	v_bfe_u32 v25, v24, 16, 1
	v_mul_f32_e32 v9, v9, v23
	v_add3_u32 v24, v24, v25, s70
	v_mul_f32_e32 v9, v36, v9
	global_store_short_d16_hi v[20:21], v24, off offset:64
	v_bfe_u32 v24, v9, 16, 1
	v_add3_u32 v9, v9, v24, s70
	global_store_short_d16_hi v[20:21], v9, off offset:128
	v_mul_f32_e32 v9, v22, v23
	v_mul_f32_e32 v9, v37, v9
	v_bfe_u32 v22, v9, 16, 1
	v_add3_u32 v9, v9, v22, s70
	global_store_short_d16_hi v[20:21], v9, off offset:192
	v_add_u32_e32 v9, v18, v8
	v_lshl_add_u32 v9, v9, 7, v138
	v_lshl_add_u32 v9, v9, 2, 0
	v_lshlrev_b64 v[18:19], 12, v[18:19]
	v_lshl_add_u64 v[18:19], v[4:5], 0, v[18:19]
	s_waitcnt lgkmcnt(1)
; __device__ __forceinline__ unsigned f2bf(float f) { unsigned u = __builtin_bit_cast(unsigned, f); return (u + 0x7fffu + ((u >> 16) & 1u)) >> 16; }
; __device__ __forceinline__ int crow(int r, int hi) { return (r & 3) + 8 * (r >> 2) + 4 * hi; }
; __device__ __forceinline__ void attn_unit(const bf16* __restrict__ Qb, const bf16* __restrict__ Kh, const bf16* __restrict__ Vh, int klat0, int nlt, int kctx0, int NT,
;                                           float lam, float post, const float* __restrict__ subw, bf16* __restrict__ Ob, char* lds) {
;     ...
;     for (int r = 0; r < 16; ++r) { const int orow = crow(r, hi_e); float v[4]; float ss = 0.f;
; #pragma unroll
;       for (int d0 = 0; d0 < 4; ++d0) { v[d0] = o[d0][r] - lam * X[(wq_e * 32 + orow) * 128 + d0 * 32 + r32_e]; ss += v[d0] * v[d0]; }
;       ss += __shfl_xor(ss, 1); ss += __shfl_xor(ss, 2); ss += __shfl_xor(ss, 4); ss += __shfl_xor(ss, 8); ss += __shfl_xor(ss, 16);
;       const float rs = 1.0f / sqrtf(ss * (1.0f / 128.0f) + LN_EPS);
; #pragma unroll
;       for (int d0 = 0; d0 < 4; ++d0) Ow[(long)orow * DM + d0 * 32 + r32_e] = (bf16)f2bf(v[d0] * rs * sw[d0]); }
	v_fma_f32 v22, -v160, v240, v72
	v_fma_f32 v23, -v160, v241, v58
	v_mul_f32_e32 v24, v23, v23
	v_fmac_f32_e32 v24, v22, v22
	s_waitcnt lgkmcnt(0)
	v_add_u32_e32 v244, v16, v8
	v_lshl_add_u32 v244, v244, 7, v138
	v_lshl_add_u32 v244, v244, 2, 0
	ds_read2_b32 v[236:237], v244 offset1:32
	ds_read2_b32 v[238:239], v244 offset0:64 offset1:96
	v_fma_f32 v9, -v160, v242, v57
	v_fmac_f32_e32 v24, v9, v9
	v_fma_f32 v20, -v160, v243, v47
	v_fmac_f32_e32 v24, v20, v20
	s_nop 1
	v_mov_b32_dpp v21, v24 quad_perm:[1,0,3,2] row_mask:0xf bank_mask:0xf
	v_add_f32_e32 v21, v24, v21
	s_nop 1
	v_mov_b32_dpp v24, v21 quad_perm:[2,3,0,1] row_mask:0xf bank_mask:0xf
	v_add_f32_e32 v21, v21, v24
	s_nop 1
	v_mov_b32_dpp v24, v21 row_half_mirror row_mask:0xf bank_mask:0xf
	v_add_f32_e32 v21, v21, v24
	s_nop 1
	v_mov_b32_dpp v24, v21 row_mirror row_mask:0xf bank_mask:0xf
	v_add_f32_e32 v21, v21, v24
	v_mov_b32_e32 v24, v21
	s_nop 1
	v_permlane16_swap_b32_e32 v21, v24
	v_add_f32_e32 v21, v21, v24
	v_fmamk_f32 v21, v21, 0x3c000000, v179
	v_cmp_gt_f32_e32 vcc, s4, v21
	v_mul_f32_e32 v24, 0x4f800000, v21
	s_nop 0
	v_cndmask_b32_e32 v21, v21, v24, vcc
	v_sqrt_f32_e32 v24, v21
	s_nop 0
	v_add_u32_e32 v25, -1, v24
	v_fma_f32 v26, -v25, v24, v21
	v_cmp_ge_f32_e64 s[0:1], 0, v26
	v_add_u32_e32 v26, 1, v24
	s_nop 0
	v_cndmask_b32_e64 v25, v24, v25, s[0:1]
	v_fma_f32 v24, -v26, v24, v21
	v_cmp_lt_f32_e64 s[0:1], 0, v24
	s_nop 1
	v_cndmask_b32_e64 v24, v25, v26, s[0:1]
	v_mul_f32_e32 v25, 0x37800000, v24
	v_cndmask_b32_e32 v24, v24, v25, vcc
	v_cmp_class_f32_e32 vcc, v21, v180
	s_nop 1
	v_cndmask_b32_e32 v21, v24, v21, vcc
	v_div_scale_f32 v24, s[0:1], v21, v21, 1.0
	v_rcp_f32_e32 v25, v24
	s_nop 0
	v_fma_f32 v26, -v24, v25, 1.0
	v_fmac_f32_e32 v25, v26, v25
	v_div_scale_f32 v26, vcc, 1.0, v21, 1.0
	v_mul_f32_e32 v27, v26, v25
	v_fma_f32 v28, -v24, v27, v26
	v_fmac_f32_e32 v27, v28, v25
	v_fma_f32 v24, -v24, v27, v26
	v_div_fmas_f32 v24, v24, v25, v27
	v_div_fixup_f32 v21, v24, v21, 1.0
	v_mul_f32_e32 v22, v22, v21
	v_mul_f32_e32 v22, v34, v22
	v_bfe_u32 v24, v22, 16, 1
	v_add3_u32 v22, v22, v24, s70
	global_store_short_d16_hi v[18:19], v22, off
	v_mul_f32_e32 v22, v23, v21
	v_mul_f32_e32 v22, v35, v22
	v_bfe_u32 v23, v22, 16, 1
	v_mul_f32_e32 v9, v9, v21
	v_add3_u32 v22, v22, v23, s70
	v_mul_f32_e32 v9, v36, v9
	global_store_short_d16_hi v[18:19], v22, off offset:64
	v_bfe_u32 v22, v9, 16, 1
	v_add3_u32 v9, v9, v22, s70
	global_store_short_d16_hi v[18:19], v9, off offset:128
	v_mul_f32_e32 v9, v20, v21
	v_mul_f32_e32 v9, v37, v9
	v_bfe_u32 v20, v9, 16, 1
	v_add3_u32 v9, v9, v20, s70
	global_store_short_d16_hi v[18:19], v9, off offset:192
	v_add_u32_e32 v9, v16, v8
	v_lshl_add_u32 v9, v9, 7, v138
	v_lshl_add_u32 v9, v9, 2, 0
	v_lshlrev_b64 v[16:17], 12, v[16:17]
	v_lshl_add_u64 v[16:17], v[4:5], 0, v[16:17]
	s_waitcnt lgkmcnt(1)
	v_fma_f32 v20, -v160, v236, v71
	v_fma_f32 v21, -v160, v237, v56
	v_mul_f32_e32 v22, v21, v21
	v_fmac_f32_e32 v22, v20, v20
	s_waitcnt lgkmcnt(0)
	v_add_u32_e32 v244, v14, v8
	v_lshl_add_u32 v244, v244, 7, v138
	v_lshl_add_u32 v244, v244, 2, 0
	ds_read2_b32 v[240:241], v244 offset1:32
	ds_read2_b32 v[242:243], v244 offset0:64 offset1:96
	v_fma_f32 v9, -v160, v238, v55
	v_fmac_f32_e32 v22, v9, v9
	v_fma_f32 v18, -v160, v239, v46
	v_fmac_f32_e32 v22, v18, v18
	s_nop 1
	v_mov_b32_dpp v19, v22 quad_perm:[1,0,3,2] row_mask:0xf bank_mask:0xf
	v_add_f32_e32 v19, v22, v19
	s_nop 1
	v_mov_b32_dpp v22, v19 quad_perm:[2,3,0,1] row_mask:0xf bank_mask:0xf
	v_add_f32_e32 v19, v19, v22
	s_nop 1
	v_mov_b32_dpp v22, v19 row_half_mirror row_mask:0xf bank_mask:0xf
	v_add_f32_e32 v19, v19, v22
	s_nop 1
	v_mov_b32_dpp v22, v19 row_mirror row_mask:0xf bank_mask:0xf
	v_add_f32_e32 v19, v19, v22
	v_mov_b32_e32 v22, v19
	s_nop 1
	v_permlane16_swap_b32_e32 v19, v22
	v_add_f32_e32 v19, v19, v22
	v_fmamk_f32 v19, v19, 0x3c000000, v179
	v_cmp_gt_f32_e32 vcc, s4, v19
	v_mul_f32_e32 v22, 0x4f800000, v19
	s_nop 0
	v_cndmask_b32_e32 v19, v19, v22, vcc
	v_sqrt_f32_e32 v22, v19
	s_nop 0
	v_add_u32_e32 v23, -1, v22
	v_fma_f32 v24, -v23, v22, v19
	v_cmp_ge_f32_e64 s[0:1], 0, v24
	v_add_u32_e32 v24, 1, v22
	s_nop 0
	v_cndmask_b32_e64 v23, v22, v23, s[0:1]
	v_fma_f32 v22, -v24, v22, v19
	v_cmp_lt_f32_e64 s[0:1], 0, v22
	s_nop 1
	v_cndmask_b32_e64 v22, v23, v24, s[0:1]
	v_mul_f32_e32 v23, 0x37800000, v22
	v_cndmask_b32_e32 v22, v22, v23, vcc
	v_cmp_class_f32_e32 vcc, v19, v180
	s_nop 1
	v_cndmask_b32_e32 v19, v22, v19, vcc
	v_div_scale_f32 v22, s[0:1], v19, v19, 1.0
	v_rcp_f32_e32 v23, v22
	s_nop 0
	v_fma_f32 v24, -v22, v23, 1.0
	v_fmac_f32_e32 v23, v24, v23
	v_div_scale_f32 v24, vcc, 1.0, v19, 1.0
	v_mul_f32_e32 v25, v24, v23
	v_fma_f32 v26, -v22, v25, v24
	v_fmac_f32_e32 v25, v26, v23
	v_fma_f32 v22, -v22, v25, v24
	v_div_fmas_f32 v22, v22, v23, v25
	v_div_fixup_f32 v19, v22, v19, 1.0
	v_mul_f32_e32 v20, v20, v19
	v_mul_f32_e32 v20, v34, v20
	v_bfe_u32 v22, v20, 16, 1
	v_add3_u32 v20, v20, v22, s70
	global_store_short_d16_hi v[16:17], v20, off
	v_mul_f32_e32 v20, v21, v19
	v_mul_f32_e32 v20, v35, v20
	v_bfe_u32 v21, v20, 16, 1
	v_mul_f32_e32 v9, v9, v19
	v_add3_u32 v20, v20, v21, s70
	v_mul_f32_e32 v9, v36, v9
	global_store_short_d16_hi v[16:17], v20, off offset:64
	v_bfe_u32 v20, v9, 16, 1
	v_add3_u32 v9, v9, v20, s70
	global_store_short_d16_hi v[16:17], v9, off offset:128
	v_mul_f32_e32 v9, v18, v19
	v_mul_f32_e32 v9, v37, v9
	v_bfe_u32 v18, v9, 16, 1
	v_add3_u32 v9, v9, v18, s70
	global_store_short_d16_hi v[16:17], v9, off offset:192
	v_add_u32_e32 v9, v14, v8
	v_lshl_add_u32 v9, v9, 7, v138
	v_lshl_add_u32 v9, v9, 2, 0
	v_lshlrev_b64 v[14:15], 12, v[14:15]
	v_lshl_add_u64 v[14:15], v[4:5], 0, v[14:15]
	s_waitcnt lgkmcnt(1)
; __device__ __forceinline__ unsigned f2bf(float f) { unsigned u = __builtin_bit_cast(unsigned, f); return (u + 0x7fffu + ((u >> 16) & 1u)) >> 16; }
; __device__ __forceinline__ int crow(int r, int hi) { return (r & 3) + 8 * (r >> 2) + 4 * hi; }
; __device__ __forceinline__ void attn_unit(const bf16* __restrict__ Qb, const bf16* __restrict__ Kh, const bf16* __restrict__ Vh, int klat0, int nlt, int kctx0, int NT,
;                                           float lam, float post, const float* __restrict__ subw, bf16* __restrict__ Ob, char* lds) {
;     ...
;     for (int r = 0; r < 16; ++r) { const int orow = crow(r, hi_e); float v[4]; float ss = 0.f;
; #pragma unroll
;       for (int d0 = 0; d0 < 4; ++d0) { v[d0] = o[d0][r] - lam * X[(wq_e * 32 + orow) * 128 + d0 * 32 + r32_e]; ss += v[d0] * v[d0]; }
;       ss += __shfl_xor(ss, 1); ss += __shfl_xor(ss, 2); ss += __shfl_xor(ss, 4); ss += __shfl_xor(ss, 8); ss += __shfl_xor(ss, 16);
;       const float rs = 1.0f / sqrtf(ss * (1.0f / 128.0f) + LN_EPS);
; #pragma unroll
;       for (int d0 = 0; d0 < 4; ++d0) Ow[(long)orow * DM + d0 * 32 + r32_e] = (bf16)f2bf(v[d0] * rs * sw[d0]); }
	v_fma_f32 v18, -v160, v240, v70
	v_fma_f32 v19, -v160, v241, v54
	v_mul_f32_e32 v20, v19, v19
	v_fmac_f32_e32 v20, v18, v18
	s_waitcnt lgkmcnt(0)
	v_add_u32_e32 v244, v12, v8
	v_lshl_add_u32 v244, v244, 7, v138
	v_lshl_add_u32 v244, v244, 2, 0
	ds_read2_b32 v[236:237], v244 offset1:32
	ds_read2_b32 v[238:239], v244 offset0:64 offset1:96
	v_fma_f32 v9, -v160, v242, v44
	v_fmac_f32_e32 v20, v9, v9
	v_fma_f32 v16, -v160, v243, v45
	v_fmac_f32_e32 v20, v16, v16
	s_nop 1
	v_mov_b32_dpp v17, v20 quad_perm:[1,0,3,2] row_mask:0xf bank_mask:0xf
	v_add_f32_e32 v17, v20, v17
	s_nop 1
	v_mov_b32_dpp v20, v17 quad_perm:[2,3,0,1] row_mask:0xf bank_mask:0xf
	v_add_f32_e32 v17, v17, v20
	s_nop 1
	v_mov_b32_dpp v20, v17 row_half_mirror row_mask:0xf bank_mask:0xf
	v_add_f32_e32 v17, v17, v20
	s_nop 1
	v_mov_b32_dpp v20, v17 row_mirror row_mask:0xf bank_mask:0xf
	v_add_f32_e32 v17, v17, v20
	v_mov_b32_e32 v20, v17
	s_nop 1
	v_permlane16_swap_b32_e32 v17, v20
	v_add_f32_e32 v17, v17, v20
	v_fmamk_f32 v17, v17, 0x3c000000, v179
	v_cmp_gt_f32_e32 vcc, s4, v17
	v_mul_f32_e32 v20, 0x4f800000, v17
	s_nop 0
	v_cndmask_b32_e32 v17, v17, v20, vcc
	v_sqrt_f32_e32 v20, v17
	s_nop 0
	v_add_u32_e32 v21, -1, v20
	v_fma_f32 v22, -v21, v20, v17
	v_cmp_ge_f32_e64 s[0:1], 0, v22
	v_add_u32_e32 v22, 1, v20
	s_nop 0
	v_cndmask_b32_e64 v21, v20, v21, s[0:1]
	v_fma_f32 v20, -v22, v20, v17
	v_cmp_lt_f32_e64 s[0:1], 0, v20
	s_nop 1
	v_cndmask_b32_e64 v20, v21, v22, s[0:1]
	v_mul_f32_e32 v21, 0x37800000, v20
	v_cndmask_b32_e32 v20, v20, v21, vcc
	v_cmp_class_f32_e32 vcc, v17, v180
	s_nop 1
	v_cndmask_b32_e32 v17, v20, v17, vcc
	v_div_scale_f32 v20, s[0:1], v17, v17, 1.0
	v_rcp_f32_e32 v21, v20
	s_nop 0
	v_fma_f32 v22, -v20, v21, 1.0
	v_fmac_f32_e32 v21, v22, v21
	v_div_scale_f32 v22, vcc, 1.0, v17, 1.0
	v_mul_f32_e32 v23, v22, v21
	v_fma_f32 v24, -v20, v23, v22
	v_fmac_f32_e32 v23, v24, v21
	v_fma_f32 v20, -v20, v23, v22
	v_div_fmas_f32 v20, v20, v21, v23
	v_div_fixup_f32 v17, v20, v17, 1.0
	v_mul_f32_e32 v18, v18, v17
	v_mul_f32_e32 v18, v34, v18
	v_bfe_u32 v20, v18, 16, 1
	v_add3_u32 v18, v18, v20, s70
	global_store_short_d16_hi v[14:15], v18, off
	v_mul_f32_e32 v18, v19, v17
	v_mul_f32_e32 v18, v35, v18
	v_bfe_u32 v19, v18, 16, 1
	v_mul_f32_e32 v9, v9, v17
	v_add3_u32 v18, v18, v19, s70
	v_mul_f32_e32 v9, v36, v9
	global_store_short_d16_hi v[14:15], v18, off offset:64
	v_bfe_u32 v18, v9, 16, 1
	v_add3_u32 v9, v9, v18, s70
	global_store_short_d16_hi v[14:15], v9, off offset:128
	v_mul_f32_e32 v9, v16, v17
	v_mul_f32_e32 v9, v37, v9
	v_bfe_u32 v16, v9, 16, 1
	v_add3_u32 v9, v9, v16, s70
	global_store_short_d16_hi v[14:15], v9, off offset:192
	v_add_u32_e32 v9, v12, v8
	v_lshl_add_u32 v9, v9, 7, v138
	v_lshl_add_u32 v9, v9, 2, 0
	v_lshlrev_b64 v[12:13], 12, v[12:13]
	v_lshl_add_u64 v[12:13], v[4:5], 0, v[12:13]
	s_waitcnt lgkmcnt(1)
	v_fma_f32 v16, -v160, v236, v69
	v_fma_f32 v17, -v160, v237, v53
	v_mul_f32_e32 v18, v17, v17
	v_fmac_f32_e32 v18, v16, v16
	s_waitcnt lgkmcnt(0)
	v_add_u32_e32 v244, v10, v8
	v_lshl_add_u32 v244, v244, 7, v138
	v_lshl_add_u32 v244, v244, 2, 0
	ds_read2_b32 v[240:241], v244 offset1:32
	ds_read2_b32 v[242:243], v244 offset0:64 offset1:96
	v_fma_f32 v9, -v160, v238, v42
	v_fmac_f32_e32 v18, v9, v9
	v_fma_f32 v14, -v160, v239, v43
	v_fmac_f32_e32 v18, v14, v14
	s_nop 1
	v_mov_b32_dpp v15, v18 quad_perm:[1,0,3,2] row_mask:0xf bank_mask:0xf
	v_add_f32_e32 v15, v18, v15
	s_nop 1
	v_mov_b32_dpp v18, v15 quad_perm:[2,3,0,1] row_mask:0xf bank_mask:0xf
	v_add_f32_e32 v15, v15, v18
	s_nop 1
	v_mov_b32_dpp v18, v15 row_half_mirror row_mask:0xf bank_mask:0xf
	v_add_f32_e32 v15, v15, v18
	s_nop 1
	v_mov_b32_dpp v18, v15 row_mirror row_mask:0xf bank_mask:0xf
	v_add_f32_e32 v15, v15, v18
	v_mov_b32_e32 v18, v15
	s_nop 1
	v_permlane16_swap_b32_e32 v15, v18
	v_add_f32_e32 v15, v15, v18
	v_fmamk_f32 v15, v15, 0x3c000000, v179
	v_cmp_gt_f32_e32 vcc, s4, v15
	v_mul_f32_e32 v18, 0x4f800000, v15
	s_nop 0
	v_cndmask_b32_e32 v15, v15, v18, vcc
	v_sqrt_f32_e32 v18, v15
	s_nop 0
	v_add_u32_e32 v19, -1, v18
	v_fma_f32 v20, -v19, v18, v15
	v_cmp_ge_f32_e64 s[0:1], 0, v20
	v_add_u32_e32 v20, 1, v18
	s_nop 0
	v_cndmask_b32_e64 v19, v18, v19, s[0:1]
	v_fma_f32 v18, -v20, v18, v15
	v_cmp_lt_f32_e64 s[0:1], 0, v18
	s_nop 1
	v_cndmask_b32_e64 v18, v19, v20, s[0:1]
	v_mul_f32_e32 v19, 0x37800000, v18
	v_cndmask_b32_e32 v18, v18, v19, vcc
	v_cmp_class_f32_e32 vcc, v15, v180
	s_nop 1
	v_cndmask_b32_e32 v15, v18, v15, vcc
	v_div_scale_f32 v18, s[0:1], v15, v15, 1.0
	v_rcp_f32_e32 v19, v18
	s_nop 0
	v_fma_f32 v20, -v18, v19, 1.0
	v_fmac_f32_e32 v19, v20, v19
	v_div_scale_f32 v20, vcc, 1.0, v15, 1.0
	v_mul_f32_e32 v21, v20, v19
	v_fma_f32 v22, -v18, v21, v20
	v_fmac_f32_e32 v21, v22, v19
	v_fma_f32 v18, -v18, v21, v20
	v_div_fmas_f32 v18, v18, v19, v21
	v_div_fixup_f32 v15, v18, v15, 1.0
	v_mul_f32_e32 v16, v16, v15
	v_mul_f32_e32 v16, v34, v16
	v_bfe_u32 v18, v16, 16, 1
	v_add3_u32 v16, v16, v18, s70
	global_store_short_d16_hi v[12:13], v16, off
	v_mul_f32_e32 v16, v17, v15
	v_mul_f32_e32 v16, v35, v16
	v_bfe_u32 v17, v16, 16, 1
	v_mul_f32_e32 v9, v9, v15
	v_add3_u32 v16, v16, v17, s70
	v_mul_f32_e32 v9, v36, v9
	global_store_short_d16_hi v[12:13], v16, off offset:64
	v_bfe_u32 v16, v9, 16, 1
	v_add3_u32 v9, v9, v16, s70
	global_store_short_d16_hi v[12:13], v9, off offset:128
	v_mul_f32_e32 v9, v14, v15
	v_mul_f32_e32 v9, v37, v9
	v_bfe_u32 v14, v9, 16, 1
	v_add3_u32 v9, v9, v14, s70
	global_store_short_d16_hi v[12:13], v9, off offset:192
	v_add_u32_e32 v9, v10, v8
	v_lshl_add_u32 v9, v9, 7, v138
	v_lshl_add_u32 v9, v9, 2, 0
	v_lshlrev_b64 v[10:11], 12, v[10:11]
	v_lshl_add_u64 v[10:11], v[4:5], 0, v[10:11]
	s_waitcnt lgkmcnt(1)
; __device__ __forceinline__ unsigned f2bf(float f) { unsigned u = __builtin_bit_cast(unsigned, f); return (u + 0x7fffu + ((u >> 16) & 1u)) >> 16; }
; __device__ __forceinline__ int crow(int r, int hi) { return (r & 3) + 8 * (r >> 2) + 4 * hi; }
; __device__ __forceinline__ void attn_unit(const bf16* __restrict__ Qb, const bf16* __restrict__ Kh, const bf16* __restrict__ Vh, int klat0, int nlt, int kctx0, int NT,
;                                           float lam, float post, const float* __restrict__ subw, bf16* __restrict__ Ob, char* lds) {
;     ...
;     for (int r = 0; r < 16; ++r) { const int orow = crow(r, hi_e); float v[4]; float ss = 0.f;
; #pragma unroll
;       for (int d0 = 0; d0 < 4; ++d0) { v[d0] = o[d0][r] - lam * X[(wq_e * 32 + orow) * 128 + d0 * 32 + r32_e]; ss += v[d0] * v[d0]; }
;       ss += __shfl_xor(ss, 1); ss += __shfl_xor(ss, 2); ss += __shfl_xor(ss, 4); ss += __shfl_xor(ss, 8); ss += __shfl_xor(ss, 16);
;       const float rs = 1.0f / sqrtf(ss * (1.0f / 128.0f) + LN_EPS);
; #pragma unroll
;       for (int d0 = 0; d0 < 4; ++d0) Ow[(long)orow * DM + d0 * 32 + r32_e] = (bf16)f2bf(v[d0] * rs * sw[d0]); }
	v_fma_f32 v14, -v160, v240, v68
	v_fma_f32 v15, -v160, v241, v52
	v_mul_f32_e32 v16, v15, v15
	v_fmac_f32_e32 v16, v14, v14
	s_waitcnt lgkmcnt(0)
	v_add_u32_e32 v244, v6, v8
	v_lshl_add_u32 v244, v244, 7, v138
	v_lshl_add_u32 v244, v244, 2, 0
	ds_read2_b32 v[236:237], v244 offset1:32
	ds_read2_b32 v[238:239], v244 offset0:64 offset1:96
	v_fma_f32 v9, -v160, v242, v40
	v_fmac_f32_e32 v16, v9, v9
	v_fma_f32 v12, -v160, v243, v41
	v_fmac_f32_e32 v16, v12, v12
	s_nop 1
	v_mov_b32_dpp v13, v16 quad_perm:[1,0,3,2] row_mask:0xf bank_mask:0xf
	v_add_f32_e32 v13, v16, v13
	s_nop 1
	v_mov_b32_dpp v16, v13 quad_perm:[2,3,0,1] row_mask:0xf bank_mask:0xf
	v_add_f32_e32 v13, v13, v16
	s_nop 1
	v_mov_b32_dpp v16, v13 row_half_mirror row_mask:0xf bank_mask:0xf
	v_add_f32_e32 v13, v13, v16
	s_nop 1
	v_mov_b32_dpp v16, v13 row_mirror row_mask:0xf bank_mask:0xf
	v_add_f32_e32 v13, v13, v16
	v_mov_b32_e32 v16, v13
	s_nop 1
	v_permlane16_swap_b32_e32 v13, v16
	v_add_f32_e32 v13, v13, v16
	v_fmamk_f32 v13, v13, 0x3c000000, v179
	v_cmp_gt_f32_e32 vcc, s4, v13
	v_mul_f32_e32 v16, 0x4f800000, v13
	s_nop 0
	v_cndmask_b32_e32 v13, v13, v16, vcc
	v_sqrt_f32_e32 v16, v13
	s_nop 0
	v_add_u32_e32 v17, -1, v16
	v_fma_f32 v18, -v17, v16, v13
	v_cmp_ge_f32_e64 s[0:1], 0, v18
	v_add_u32_e32 v18, 1, v16
	s_nop 0
	v_cndmask_b32_e64 v17, v16, v17, s[0:1]
	v_fma_f32 v16, -v18, v16, v13
	v_cmp_lt_f32_e64 s[0:1], 0, v16
	s_nop 1
	v_cndmask_b32_e64 v16, v17, v18, s[0:1]
	v_mul_f32_e32 v17, 0x37800000, v16
	v_cndmask_b32_e32 v16, v16, v17, vcc
	v_cmp_class_f32_e32 vcc, v13, v180
	s_nop 1
	v_cndmask_b32_e32 v13, v16, v13, vcc
	v_div_scale_f32 v16, s[0:1], v13, v13, 1.0
	v_rcp_f32_e32 v17, v16
	s_nop 0
	v_fma_f32 v18, -v16, v17, 1.0
	v_fmac_f32_e32 v17, v18, v17
	v_div_scale_f32 v18, vcc, 1.0, v13, 1.0
	v_mul_f32_e32 v19, v18, v17
	v_fma_f32 v20, -v16, v19, v18
	v_fmac_f32_e32 v19, v20, v17
	v_fma_f32 v16, -v16, v19, v18
	v_div_fmas_f32 v16, v16, v17, v19
	v_div_fixup_f32 v13, v16, v13, 1.0
	v_mul_f32_e32 v14, v14, v13
	v_mul_f32_e32 v14, v34, v14
	v_bfe_u32 v16, v14, 16, 1
	v_add3_u32 v14, v14, v16, s70
	global_store_short_d16_hi v[10:11], v14, off
	v_mul_f32_e32 v14, v15, v13
	v_mul_f32_e32 v14, v35, v14
	v_bfe_u32 v15, v14, 16, 1
	v_mul_f32_e32 v9, v9, v13
	v_add3_u32 v14, v14, v15, s70
	v_mul_f32_e32 v9, v36, v9
	global_store_short_d16_hi v[10:11], v14, off offset:64
	v_bfe_u32 v14, v9, 16, 1
	v_add3_u32 v9, v9, v14, s70
	global_store_short_d16_hi v[10:11], v9, off offset:128
	v_mul_f32_e32 v9, v12, v13
	v_mul_f32_e32 v9, v37, v9
	v_bfe_u32 v12, v9, 16, 1
	v_add3_u32 v9, v9, v12, s70
	global_store_short_d16_hi v[10:11], v9, off offset:192
	v_add_u32_e32 v9, v6, v8
	v_lshl_add_u32 v9, v9, 7, v138
	v_lshl_add_u32 v9, v9, 2, 0
	v_lshlrev_b64 v[6:7], 12, v[6:7]
	v_lshl_add_u64 v[6:7], v[4:5], 0, v[6:7]
	s_waitcnt lgkmcnt(1)
	v_fma_f32 v12, -v160, v236, v67
	v_fma_f32 v13, -v160, v237, v51
	v_mul_f32_e32 v14, v13, v13
	v_fmac_f32_e32 v14, v12, v12
	s_waitcnt lgkmcnt(0)
; __device__ __forceinline__ unsigned f2bf(float f) { unsigned u = __builtin_bit_cast(unsigned, f); return (u + 0x7fffu + ((u >> 16) & 1u)) >> 16; }
; __device__ __forceinline__ int crow(int r, int hi) { return (r & 3) + 8 * (r >> 2) + 4 * hi; }
; __device__ __forceinline__ void attn_unit(const bf16* __restrict__ Qb, const bf16* __restrict__ Kh, const bf16* __restrict__ Vh, int klat0, int nlt, int kctx0, int NT,
;                                           float lam, float post, const float* __restrict__ subw, bf16* __restrict__ Ob, char* lds) {
;     ...
;     for (int r = 0; r < 16; ++r) { const int orow = crow(r, hi_e); float v[4]; float ss = 0.f;
; #pragma unroll
;       for (int d0 = 0; d0 < 4; ++d0) { v[d0] = o[d0][r] - lam * X[(wq_e * 32 + orow) * 128 + d0 * 32 + r32_e]; ss += v[d0] * v[d0]; }
;       ss += __shfl_xor(ss, 1); ss += __shfl_xor(ss, 2); ss += __shfl_xor(ss, 4); ss += __shfl_xor(ss, 8); ss += __shfl_xor(ss, 16);
;       const float rs = 1.0f / sqrtf(ss * (1.0f / 128.0f) + LN_EPS);
; #pragma unroll
;       for (int d0 = 0; d0 < 4; ++d0) Ow[(long)orow * DM + d0 * 32 + r32_e] = (bf16)f2bf(v[d0] * rs * sw[d0]); }
	v_add_u32_e32 v245, v2, v8
	v_lshl_add_u32 v245, v245, 7, v138
	v_lshl_add_u32 v244, v245, 2, 0
	ds_read2_b32 v[240:241], v244 offset1:32
	ds_read2_b32 v[242:243], v244 offset0:64 offset1:96
	v_fma_f32 v9, -v160, v238, v38
	v_fmac_f32_e32 v14, v9, v9
	v_fma_f32 v10, -v160, v239, v39
	v_fmac_f32_e32 v14, v10, v10
	s_nop 1
	v_mov_b32_dpp v11, v14 quad_perm:[1,0,3,2] row_mask:0xf bank_mask:0xf
	v_add_f32_e32 v11, v14, v11
	s_nop 1
	v_mov_b32_dpp v14, v11 quad_perm:[2,3,0,1] row_mask:0xf bank_mask:0xf
	v_add_f32_e32 v11, v11, v14
	s_nop 1
	v_mov_b32_dpp v14, v11 row_half_mirror row_mask:0xf bank_mask:0xf
	v_add_f32_e32 v11, v11, v14
	s_nop 1
	v_mov_b32_dpp v14, v11 row_mirror row_mask:0xf bank_mask:0xf
	v_add_f32_e32 v11, v11, v14
	v_mov_b32_e32 v14, v11
	s_nop 1
	v_permlane16_swap_b32_e32 v11, v14
	v_add_f32_e32 v11, v11, v14
	v_fmamk_f32 v11, v11, 0x3c000000, v179
	v_cmp_gt_f32_e32 vcc, s4, v11
	v_mul_f32_e32 v14, 0x4f800000, v11
	s_nop 0
	v_cndmask_b32_e32 v11, v11, v14, vcc
	v_sqrt_f32_e32 v14, v11
	s_nop 0
	v_add_u32_e32 v15, -1, v14
	v_fma_f32 v16, -v15, v14, v11
	v_cmp_ge_f32_e64 s[0:1], 0, v16
	v_add_u32_e32 v16, 1, v14
	s_nop 0
	v_cndmask_b32_e64 v15, v14, v15, s[0:1]
	v_fma_f32 v14, -v16, v14, v11
	v_cmp_lt_f32_e64 s[0:1], 0, v14
	s_nop 1
	v_cndmask_b32_e64 v14, v15, v16, s[0:1]
	v_mul_f32_e32 v15, 0x37800000, v14
	v_cndmask_b32_e32 v14, v14, v15, vcc
	v_cmp_class_f32_e32 vcc, v11, v180
	s_nop 1
	v_cndmask_b32_e32 v11, v14, v11, vcc
	v_div_scale_f32 v14, s[0:1], v11, v11, 1.0
	v_rcp_f32_e32 v15, v14
	s_nop 0
	v_fma_f32 v16, -v14, v15, 1.0
	v_fmac_f32_e32 v15, v16, v15
	v_div_scale_f32 v16, vcc, 1.0, v11, 1.0
	v_mul_f32_e32 v17, v16, v15
	v_fma_f32 v18, -v14, v17, v16
	v_fmac_f32_e32 v17, v18, v15
	v_fma_f32 v14, -v14, v17, v16
	v_div_fmas_f32 v14, v14, v15, v17
	v_div_fixup_f32 v11, v14, v11, 1.0
	v_mul_f32_e32 v12, v12, v11
	v_mul_f32_e32 v12, v34, v12
	v_bfe_u32 v14, v12, 16, 1
	v_add3_u32 v12, v12, v14, s70
	global_store_short_d16_hi v[6:7], v12, off
	v_mul_f32_e32 v12, v13, v11
	v_mul_f32_e32 v12, v35, v12
	v_bfe_u32 v13, v12, 16, 1
	v_mul_f32_e32 v9, v9, v11
	v_add3_u32 v12, v12, v13, s70
	v_mul_f32_e32 v9, v36, v9
	global_store_short_d16_hi v[6:7], v12, off offset:64
	v_bfe_u32 v12, v9, 16, 1
	v_add3_u32 v9, v9, v12, s70
	global_store_short_d16_hi v[6:7], v9, off offset:128
	v_mul_f32_e32 v9, v10, v11
	v_mul_f32_e32 v9, v37, v9
	v_bfe_u32 v10, v9, 16, 1
	v_add3_u32 v9, v9, v10, s70
	global_store_short_d16_hi v[6:7], v9, off offset:192
	v_add_u32_e32 v6, v2, v8
	v_lshl_add_u32 v6, v6, 7, v138
	v_lshl_add_u32 v8, v6, 2, 0
	v_lshlrev_b64 v[2:3], 12, v[2:3]
	v_lshl_add_u64 v[2:3], v[4:5], 0, v[2:3]
	s_waitcnt lgkmcnt(1)
	v_fma_f32 v9, -v160, v240, v66
	v_fma_f32 v10, -v160, v241, v50
	v_mul_f32_e32 v11, v10, v10
	v_fmac_f32_e32 v11, v9, v9
	s_waitcnt lgkmcnt(0)
	v_fma_f32 v6, -v160, v242, v32
	v_fmac_f32_e32 v11, v6, v6
	v_fma_f32 v7, -v160, v243, v33
	v_fmac_f32_e32 v11, v7, v7
	s_nop 1
	v_mov_b32_dpp v8, v11 quad_perm:[1,0,3,2] row_mask:0xf bank_mask:0xf
	s_waitcnt lgkmcnt(0)
	v_add_f32_e32 v8, v11, v8
	s_nop 1
	v_mov_b32_dpp v11, v8 quad_perm:[2,3,0,1] row_mask:0xf bank_mask:0xf
	s_waitcnt lgkmcnt(0)
	v_add_f32_e32 v8, v8, v11
	s_nop 1
	v_mov_b32_dpp v11, v8 row_half_mirror row_mask:0xf bank_mask:0xf
	s_waitcnt lgkmcnt(0)
	v_add_f32_e32 v8, v8, v11
	s_nop 1
	v_mov_b32_dpp v11, v8 row_mirror row_mask:0xf bank_mask:0xf
	s_waitcnt lgkmcnt(0)
	v_add_f32_e32 v8, v8, v11
	v_mov_b32_e32 v11, v8
	s_nop 1
	v_permlane16_swap_b32_e32 v8, v11
	s_waitcnt lgkmcnt(0)
	v_add_f32_e32 v8, v8, v11
	v_fmamk_f32 v8, v8, 0x3c000000, v179
	v_cmp_gt_f32_e32 vcc, s4, v8
	v_mul_f32_e32 v11, 0x4f800000, v8
	s_nop 0
	v_cndmask_b32_e32 v8, v8, v11, vcc
	v_sqrt_f32_e32 v11, v8
	s_nop 0
	v_add_u32_e32 v12, -1, v11
	v_fma_f32 v13, -v12, v11, v8
	v_cmp_ge_f32_e64 s[0:1], 0, v13
	v_add_u32_e32 v13, 1, v11
	s_nop 0
	v_cndmask_b32_e64 v12, v11, v12, s[0:1]
	v_fma_f32 v11, -v13, v11, v8
	v_cmp_lt_f32_e64 s[0:1], 0, v11
	s_nop 1
	v_cndmask_b32_e64 v11, v12, v13, s[0:1]
	v_mul_f32_e32 v12, 0x37800000, v11
	v_cndmask_b32_e32 v11, v11, v12, vcc
	v_cmp_class_f32_e32 vcc, v8, v180
	s_nop 1
	v_cndmask_b32_e32 v8, v11, v8, vcc
	v_div_scale_f32 v11, s[0:1], v8, v8, 1.0
	v_rcp_f32_e32 v12, v11
	s_nop 0
	v_fma_f32 v13, -v11, v12, 1.0
	v_fmac_f32_e32 v12, v13, v12
	v_div_scale_f32 v13, vcc, 1.0, v8, 1.0
	v_mul_f32_e32 v14, v13, v12
	v_fma_f32 v15, -v11, v14, v13
	v_fmac_f32_e32 v14, v15, v12
	v_fma_f32 v11, -v11, v14, v13
	v_div_fmas_f32 v11, v11, v12, v14
	v_div_fixup_f32 v8, v11, v8, 1.0
	v_mul_f32_e32 v4, v9, v8
	v_mul_f32_e32 v4, v34, v4
	v_bfe_u32 v5, v4, 16, 1
	v_add3_u32 v4, v4, v5, s70
	global_store_short_d16_hi v[2:3], v4, off
	v_mul_f32_e32 v4, v10, v8
	v_mul_f32_e32 v4, v35, v4
	v_bfe_u32 v5, v4, 16, 1
	v_add3_u32 v4, v4, v5, s70
	global_store_short_d16_hi v[2:3], v4, off offset:64
	v_mul_f32_e32 v4, v6, v8
	v_mul_f32_e32 v4, v36, v4
	v_bfe_u32 v5, v4, 16, 1
	v_add3_u32 v4, v4, v5, s70
	global_store_short_d16_hi v[2:3], v4, off offset:128
	v_mul_f32_e32 v4, v7, v8
	v_mul_f32_e32 v4, v37, v4
	v_bfe_u32 v5, v4, 16, 1
	v_add3_u32 v4, v4, v5, s70
	global_store_short_d16_hi v[2:3], v4, off offset:192
	s_branch .LBB0_714
